# attention: waves 4-7 delayed by s_sleep 10 (~640 cyc) after each task-start barrier (stagger SIMD partners so MFMA and VALU phases overlap); on top of v022
# baseline (speedup 1.0000x reference)
.LBB0_461:
	s_waitcnt lgkmcnt(0)
	s_barrier
	s_bitcmp1_b32 s33, 2
	s_cbranch_scc0 .Lstag_LBB0_461
	s_sleep 10

.Lstag_LBB0_1240:
	v_mov_b32_e32 v5, s98
	v_cndmask_b32_e64 v0, 0, v190, s[12:13]
	v_fmac_f32_e32 v0, -0.5, v4
	v_exp_f32_e32 v0, v0
	s_add_i32 s12, s88, s63
	v_mul_f32_e32 v97, 0x3fb8aa3b, v5
	v_ldexp_f32 v0, v0, s17
	v_mul_f32_e32 v72, 0x3fb8aa3b, v0
	v_add_u32_e32 v0, v167, v168
	v_mov_b32_e32 v214, v169
	ds_read_b128 v[192:195], v0
	ds_read_b128 v[154:157], v0 offset:32
	ds_read_b128 v[150:153], v0 offset:64
	ds_read_b128 v[146:149], v0 offset:96
	s_cmpk_gt_i32 s12, 0x7f
	v_cvt_f32_i32_e32 v0, v214
	v_mul_f32_e32 v9, 0, v72
	s_cselect_b64 vcc, -1, 0
	v_cndmask_b32_e32 v10, v191, v9, vcc
	v_mul_f32_e64 v8, -v72, v0
	v_fma_f32 v205, -v72, v0, v72
	ds_read_b128 v[0:3], v179
	ds_read_b128 v[4:7], v179 offset:32
	v_fma_f32 v204, 0, v72, v8
	v_pk_fma_f32 v[206:207], v[72:73], s[18:19], v[8:9] op_sel_hi:[0,1,0]
	v_pk_fma_f32 v[208:209], v[72:73], s[30:31], v[8:9] op_sel_hi:[0,1,0]
	v_pk_fma_f32 v[210:211], v[72:73], s[36:37], v[8:9] op_sel_hi:[0,1,0]
	v_pk_fma_f32 v[212:213], v[72:73], s[44:45], v[8:9] op_sel_hi:[0,1,0]
	v_pk_fma_f32 v[74:75], v[72:73], s[46:47], v[8:9] op_sel_hi:[0,1,0]
	v_pk_fma_f32 v[76:77], v[72:73], s[48:49], v[8:9] op_sel_hi:[0,1,0]
	v_pk_fma_f32 v[78:79], v[72:73], s[52:53], v[8:9] op_sel_hi:[0,1,0]
	v_pk_add_f32 v[62:63], v[10:11], v[78:79] op_sel_hi:[0,1]
	v_pk_add_f32 v[60:61], v[10:11], v[76:77] op_sel_hi:[0,1]
	v_pk_add_f32 v[58:59], v[10:11], v[74:75] op_sel_hi:[0,1]
	v_pk_add_f32 v[56:57], v[10:11], v[212:213] op_sel_hi:[0,1]
	v_pk_add_f32 v[54:55], v[10:11], v[210:211] op_sel_hi:[0,1]
	v_pk_add_f32 v[52:53], v[10:11], v[208:209] op_sel_hi:[0,1]
	v_pk_add_f32 v[50:51], v[10:11], v[206:207] op_sel_hi:[0,1]
	v_pk_add_f32 v[48:49], v[10:11], v[204:205] op_sel_hi:[0,1]
	s_cmpk_gt_i32 s12, 0x5f
	v_mul_f32_e32 v12, 0x42000000, v72
	s_waitcnt lgkmcnt(1)
	v_mfma_f32_32x32x16_bf16 v[48:63], v[0:3], v[192:195], v[48:63]
	s_cselect_b64 vcc, -1, 0
	v_cndmask_b32_e32 v12, v191, v12, vcc
	v_add_f32_e64 v46, v12, v78
	v_add_f32_e64 v47, v12, v79
	v_add_f32_e64 v44, v12, v76
	v_add_f32_e64 v45, v12, v77
	v_pk_add_f32 v[42:43], v[12:13], v[74:75] op_sel_hi:[0,1]
	v_pk_add_f32 v[40:41], v[12:13], v[212:213] op_sel_hi:[0,1]
	v_pk_add_f32 v[38:39], v[12:13], v[210:211] op_sel_hi:[0,1]
	s_waitcnt lgkmcnt(0)
	v_mfma_f32_32x32x16_bf16 v[48:63], v[4:7], v[154:157], v[48:63]
	ds_read_b128 v[0:3], v179 offset:64
	ds_read_b128 v[4:7], v179 offset:96
	v_add_f32_e64 v36, v12, v208
	v_add_f32_e64 v37, v12, v209
	v_add_f32_e64 v34, v12, v206
	v_add_f32_e64 v35, v12, v207
	v_pk_add_f32 v[32:33], v[12:13], v[204:205] op_sel_hi:[0,1]
	s_cmp_gt_i32 s12, 63
	v_mul_f32_e32 v12, 0x42800000, v72
	s_cselect_b64 vcc, -1, 0
	s_waitcnt lgkmcnt(1)
	v_mfma_f32_32x32x16_bf16 v[48:63], v[0:3], v[150:153], v[48:63]
	ds_read_b128 v[0:3], v181
	ds_read_b128 v[8:11], v181 offset:32
	v_cndmask_b32_e32 v12, v191, v12, vcc
	v_add_f32_e64 v30, v12, v78
	v_add_f32_e64 v31, v12, v79
	v_pk_add_f32 v[28:29], v[12:13], v[76:77] op_sel_hi:[0,1]
	v_pk_add_f32 v[26:27], v[12:13], v[74:75] op_sel_hi:[0,1]
	v_pk_add_f32 v[24:25], v[12:13], v[212:213] op_sel_hi:[0,1]
	v_pk_add_f32 v[22:23], v[12:13], v[210:211] op_sel_hi:[0,1]
	s_waitcnt lgkmcnt(1)
	v_mfma_f32_32x32x16_bf16 v[32:47], v[0:3], v[192:195], v[32:47]
	v_add_f32_e64 v20, v12, v208
	v_add_f32_e64 v21, v12, v209
	v_add_f32_e64 v18, v12, v206
	v_add_f32_e64 v19, v12, v207
	v_add_f32_e64 v16, v12, v204
	v_add_f32_e64 v17, v12, v205
	s_cmp_gt_i32 s12, 31
	s_cselect_b64 vcc, -1, 0
	s_cmp_gt_i32 s12, -1
	s_waitcnt lgkmcnt(0)
	v_mfma_f32_32x32x16_bf16 v[32:47], v[8:11], v[154:157], v[32:47]
	v_mfma_f32_32x32x16_bf16 v[48:63], v[4:7], v[146:149], v[48:63]
	ds_read_b128 v[0:3], v181 offset:64
	ds_read_b128 v[4:7], v181 offset:96
	s_waitcnt lgkmcnt(1)
	v_mfma_f32_32x32x16_bf16 v[32:47], v[0:3], v[150:153], v[32:47]
	ds_read_b128 v[0:3], v184
	ds_read_b128 v[8:11], v184 offset:32
	s_waitcnt lgkmcnt(1)
	v_mfma_f32_32x32x16_bf16 v[16:31], v[0:3], v[192:195], v[16:31]
	s_waitcnt lgkmcnt(0)
	v_mfma_f32_32x32x16_bf16 v[16:31], v[8:11], v[154:157], v[16:31]
	v_mfma_f32_32x32x16_bf16 v[32:47], v[4:7], v[146:149], v[32:47]
	ds_read_b128 v[0:3], v184 offset:64
	ds_read_b128 v[4:7], v184 offset:96
	ds_read_b128 v[64:67], v185
	ds_read_b128 v[68:71], v185 offset:32
	s_waitcnt lgkmcnt(3)
	v_mfma_f32_32x32x16_bf16 v[16:31], v[0:3], v[150:153], v[16:31]
	v_mul_f32_e32 v0, 0x42c00000, v72
	v_cndmask_b32_e32 v0, v191, v0, vcc
	v_add_f32_e64 v14, v0, v78
	v_add_f32_e64 v15, v0, v79
	v_add_f32_e64 v12, v0, v76
	v_add_f32_e64 v13, v0, v77
	v_pk_add_f32 v[10:11], v[0:1], v[74:75] op_sel_hi:[0,1]
	v_pk_add_f32 v[8:9], v[0:1], v[212:213] op_sel_hi:[0,1]
	v_pk_add_f32 v[2:3], v[0:1], v[206:207] op_sel_hi:[0,1]
	s_waitcnt lgkmcnt(2)
	v_mfma_f32_32x32x16_bf16 v[16:31], v[4:7], v[146:149], v[16:31]
	v_add_f32_e64 v6, v0, v210
	v_add_f32_e64 v7, v0, v211
	v_add_f32_e64 v4, v0, v208
	v_add_f32_e64 v5, v0, v209
	v_pk_add_f32 v[0:1], v[0:1], v[204:205] op_sel_hi:[0,1]
	s_cselect_b64 vcc, -1, 0
	s_waitcnt lgkmcnt(1)
	v_mfma_f32_32x32x16_bf16 v[0:15], v[64:67], v[192:195], v[0:15]
	s_waitcnt lgkmcnt(0)
	v_mfma_f32_32x32x16_bf16 v[0:15], v[68:71], v[154:157], v[0:15]
	ds_read_b128 v[64:67], v185 offset:64
	ds_read_b128 v[68:71], v185 offset:96
	ds_read_b128 v[196:199], v186
	ds_read_b128 v[200:203], v186 offset:32
	s_waitcnt lgkmcnt(3)
	v_mfma_f32_32x32x16_bf16 v[0:15], v[64:67], v[150:153], v[0:15]
	v_mul_f32_e32 v64, 0x43000000, v72
	v_cndmask_b32_e32 v64, v191, v64, vcc
	v_add_f32_e64 v78, v64, v78
	v_add_f32_e64 v79, v64, v79
	v_add_f32_e64 v76, v64, v76
	v_add_f32_e64 v77, v64, v77
	v_pk_add_f32 v[74:75], v[64:65], v[74:75] op_sel_hi:[0,1]
	v_pk_add_f32 v[72:73], v[64:65], v[212:213] op_sel_hi:[0,1]
	v_pk_add_f32 v[66:67], v[64:65], v[206:207] op_sel_hi:[0,1]
	s_waitcnt lgkmcnt(2)
	v_mfma_f32_32x32x16_bf16 v[0:15], v[68:71], v[146:149], v[0:15]
	v_add_f32_e64 v70, v64, v210
	v_add_f32_e64 v71, v64, v211
	v_add_f32_e64 v68, v64, v208
	v_add_f32_e64 v69, v64, v209
	v_pk_add_f32 v[64:65], v[64:65], v[204:205] op_sel_hi:[0,1]
	s_waitcnt lgkmcnt(1)
	s_nop 0
	v_mfma_f32_32x32x16_bf16 v[64:79], v[196:199], v[192:195], v[64:79]
	s_waitcnt lgkmcnt(0)
	v_mfma_f32_32x32x16_bf16 v[64:79], v[200:203], v[154:157], v[64:79]
	ds_read_b128 v[154:157], v186 offset:64
	ds_read_b128 v[192:195], v186 offset:96
	s_waitcnt lgkmcnt(1)
	v_mfma_f32_32x32x16_bf16 v[64:79], v[154:157], v[150:153], v[64:79]
	s_waitcnt lgkmcnt(0)
	v_mfma_f32_32x32x16_bf16 v[64:79], v[192:195], v[146:149], v[64:79]
	v_cmp_gt_i32_e32 vcc, s65, v214
	s_nop 1
	v_cndmask_b32_e32 v48, v191, v48, vcc
	s_nop 7
	v_cndmask_b32_e32 v152, v64, v191, vcc
	v_cmp_gt_i32_e32 vcc, s68, v214
	s_nop 1
	v_cndmask_b32_e32 v49, v191, v49, vcc
	v_cndmask_b32_e32 v153, v65, v191, vcc
	v_cmp_gt_i32_e32 vcc, s69, v214
	v_max3_f32 v64, v48, s67, v49
	s_nop 0
	v_cndmask_b32_e32 v50, v191, v50, vcc
	v_cndmask_b32_e32 v150, v66, v191, vcc
	v_cmp_gt_i32_e32 vcc, s70, v214
	s_nop 1
	v_cndmask_b32_e32 v51, v191, v51, vcc
	v_cndmask_b32_e32 v151, v67, v191, vcc
	v_cmp_gt_i32_e32 vcc, s71, v214
	v_max3_f32 v64, v64, v50, v51
	s_nop 0
	v_cndmask_b32_e32 v52, v191, v52, vcc
	v_cndmask_b32_e32 v148, v68, v191, vcc
	v_cmp_gt_i32_e32 vcc, s72, v214
	s_nop 1
	v_cndmask_b32_e32 v53, v191, v53, vcc
	v_cndmask_b32_e32 v149, v69, v191, vcc
	v_cmp_gt_i32_e32 vcc, s73, v214
	v_max3_f32 v64, v64, v52, v53
	s_nop 0
	v_cndmask_b32_e32 v54, v191, v54, vcc
	v_cndmask_b32_e32 v146, v70, v191, vcc
	v_cmp_gt_i32_e32 vcc, s74, v214
	s_nop 1
	v_cndmask_b32_e32 v55, v191, v55, vcc
	v_cndmask_b32_e32 v147, v71, v191, vcc
	v_cmp_gt_i32_e32 vcc, s64, v214
	v_max3_f32 v64, v64, v54, v55
	s_nop 0
	v_cndmask_b32_e32 v56, v191, v56, vcc
	v_cndmask_b32_e32 v72, v72, v191, vcc
	v_cmp_gt_i32_e32 vcc, s75, v214
	s_nop 1
	v_cndmask_b32_e32 v57, v191, v57, vcc
	v_cndmask_b32_e32 v73, v73, v191, vcc
	v_cmp_gt_i32_e32 vcc, s76, v214
	v_max3_f32 v64, v64, v56, v57
	s_nop 0
	v_cndmask_b32_e32 v58, v191, v58, vcc
	v_cndmask_b32_e32 v70, v74, v191, vcc
	v_cmp_gt_i32_e32 vcc, s77, v214
	s_nop 1
	v_cndmask_b32_e32 v59, v191, v59, vcc
	v_cndmask_b32_e32 v71, v75, v191, vcc
	v_cmp_gt_i32_e32 vcc, s82, v214
	v_max3_f32 v64, v64, v58, v59
	s_nop 0
	v_cndmask_b32_e32 v60, v191, v60, vcc
	v_cndmask_b32_e32 v68, v76, v191, vcc
	v_cmp_gt_i32_e32 vcc, s83, v214
	s_nop 1
	v_cndmask_b32_e32 v61, v191, v61, vcc
	v_cndmask_b32_e32 v69, v77, v191, vcc
	v_cmp_gt_i32_e32 vcc, s84, v214
	v_max3_f32 v64, v64, v60, v61
	s_nop 0
	v_cndmask_b32_e32 v62, v191, v62, vcc
	v_cndmask_b32_e32 v66, v78, v191, vcc
	v_cmp_gt_i32_e32 vcc, s85, v214
	s_nop 1
	v_cndmask_b32_e32 v63, v191, v63, vcc
	v_max3_f32 v64, v64, v62, v63
	v_max3_f32 v64, v64, v32, v33
	v_max3_f32 v64, v64, v34, v35
	v_max3_f32 v64, v64, v36, v37
	v_max3_f32 v64, v64, v38, v39
	v_max3_f32 v64, v64, v40, v41
	v_max3_f32 v64, v64, v42, v43
	v_max3_f32 v64, v64, v44, v45
	v_max3_f32 v64, v64, v46, v47
	v_max3_f32 v64, v64, v16, v17
	v_max3_f32 v64, v64, v18, v19
	v_max3_f32 v64, v64, v20, v21
	v_max3_f32 v64, v64, v22, v23
	v_max3_f32 v64, v64, v24, v25
	v_max3_f32 v64, v64, v26, v27
	v_max3_f32 v64, v64, v28, v29
	v_max3_f32 v64, v64, v30, v31
	v_max3_f32 v64, v64, v0, v1
	v_max3_f32 v64, v64, v2, v3
	v_max3_f32 v64, v64, v4, v5
	v_max3_f32 v64, v64, v6, v7
	v_max3_f32 v64, v64, v8, v9
	v_max3_f32 v64, v64, v10, v11
	v_max3_f32 v64, v64, v12, v13
	v_max3_f32 v64, v64, v14, v15
	v_max3_f32 v64, v64, v152, v153
	v_max3_f32 v64, v64, v150, v151
	v_max3_f32 v64, v64, v148, v149
	v_max3_f32 v64, v64, v146, v147
	v_max3_f32 v64, v64, v72, v73
	v_max3_f32 v64, v64, v70, v71
	v_cndmask_b32_e32 v67, v79, v191, vcc
	v_max3_f32 v64, v64, v68, v69
	v_max3_f32 v64, v64, v66, v67
	v_and_b32_e32 v74, 64, v187
	v_xor_b32_e32 v65, 32, v187
	v_add_u32_e32 v74, 64, v74
	v_cmp_lt_i32_e32 vcc, v65, v74
	s_nop 1
	v_cndmask_b32_e32 v65, v187, v65, vcc
	v_lshlrev_b32_e32 v65, 2, v65
	ds_bpermute_b32 v74, v65, v64
	s_waitcnt lgkmcnt(0)
	v_max3_f32 v64, v64, v74, v97
	v_pk_add_f32 v[48:49], v[48:49], v[64:65] op_sel_hi:[1,0] neg_lo:[0,1] neg_hi:[0,1]
	v_pk_add_f32 v[50:51], v[50:51], v[64:65] op_sel_hi:[1,0] neg_lo:[0,1] neg_hi:[0,1]
	v_exp_f32_e32 v48, v48
	v_exp_f32_e32 v49, v49
	v_exp_f32_e32 v50, v50
	v_exp_f32_e32 v51, v51
	v_pk_add_f32 v[52:53], v[52:53], v[64:65] op_sel_hi:[1,0] neg_lo:[0,1] neg_hi:[0,1]
	v_pk_add_f32 v[54:55], v[54:55], v[64:65] op_sel_hi:[1,0] neg_lo:[0,1] neg_hi:[0,1]
	v_exp_f32_e32 v52, v52
	v_exp_f32_e32 v53, v53
	v_exp_f32_e32 v54, v54
	v_exp_f32_e32 v55, v55
	v_pk_add_f32 v[56:57], v[56:57], v[64:65] op_sel_hi:[1,0] neg_lo:[0,1] neg_hi:[0,1]
	v_pk_add_f32 v[74:75], v[48:49], 0 op_sel_hi:[1,0]
	v_exp_f32_e32 v56, v56
	v_exp_f32_e32 v57, v57
	v_pk_add_f32 v[74:75], v[50:51], v[74:75]
	v_cvt_pk_bf16_f32 v48, v48, v49
	v_cvt_pk_bf16_f32 v49, v50, v51
	v_cvt_pk_bf16_f32 v50, v52, v53
	v_pk_add_f32 v[58:59], v[58:59], v[64:65] op_sel_hi:[1,0] neg_lo:[0,1] neg_hi:[0,1]
	v_pk_add_f32 v[74:75], v[52:53], v[74:75]
	v_exp_f32_e32 v58, v58
	v_pk_add_f32 v[52:53], v[54:55], v[74:75]
	v_exp_f32_e32 v59, v59
	v_cvt_pk_bf16_f32 v51, v54, v55
	v_pk_add_f32 v[54:55], v[56:57], v[52:53]
	v_cvt_pk_bf16_f32 v52, v56, v57
	v_pk_add_f32 v[56:57], v[60:61], v[64:65] op_sel_hi:[1,0] neg_lo:[0,1] neg_hi:[0,1]
	v_pk_add_f32 v[60:61], v[62:63], v[64:65] op_sel_hi:[1,0] neg_lo:[0,1] neg_hi:[0,1]
	v_exp_f32_e32 v56, v56
	v_exp_f32_e32 v57, v57
	v_exp_f32_e32 v60, v60
	v_exp_f32_e32 v61, v61
	v_pk_add_f32 v[54:55], v[58:59], v[54:55]
	v_cvt_pk_bf16_f32 v53, v58, v59
	s_nop 0
	v_pk_add_f32 v[58:59], v[56:57], v[54:55]
	v_cvt_pk_bf16_f32 v54, v56, v57
	v_cvt_pk_bf16_f32 v55, v60, v61
	s_nop 0
	v_pk_add_f32 v[56:57], v[60:61], v[58:59]
	v_pk_add_f32 v[32:33], v[32:33], v[64:65] op_sel_hi:[1,0] neg_lo:[0,1] neg_hi:[0,1]
	v_pk_add_f32 v[34:35], v[34:35], v[64:65] op_sel_hi:[1,0] neg_lo:[0,1] neg_hi:[0,1]
	v_exp_f32_e32 v32, v32
	v_exp_f32_e32 v33, v33
	v_exp_f32_e32 v34, v34
	v_exp_f32_e32 v35, v35
	v_pk_add_f32 v[36:37], v[36:37], v[64:65] op_sel_hi:[1,0] neg_lo:[0,1] neg_hi:[0,1]
	v_pk_add_f32 v[38:39], v[38:39], v[64:65] op_sel_hi:[1,0] neg_lo:[0,1] neg_hi:[0,1]
	v_exp_f32_e32 v36, v36
	v_exp_f32_e32 v37, v37
	v_exp_f32_e32 v38, v38
	v_exp_f32_e32 v39, v39
	v_pk_add_f32 v[40:41], v[40:41], v[64:65] op_sel_hi:[1,0] neg_lo:[0,1] neg_hi:[0,1]
	v_pk_add_f32 v[56:57], v[32:33], v[56:57]
	v_exp_f32_e32 v40, v40
	v_exp_f32_e32 v41, v41
	v_pk_add_f32 v[56:57], v[34:35], v[56:57]
	v_cvt_pk_bf16_f32 v32, v32, v33
	v_cvt_pk_bf16_f32 v33, v34, v35
	v_cvt_pk_bf16_f32 v34, v36, v37
	v_pk_add_f32 v[42:43], v[42:43], v[64:65] op_sel_hi:[1,0] neg_lo:[0,1] neg_hi:[0,1]
	v_pk_add_f32 v[56:57], v[36:37], v[56:57]
	v_exp_f32_e32 v42, v42
	v_pk_add_f32 v[36:37], v[38:39], v[56:57]
	v_exp_f32_e32 v43, v43
	v_cvt_pk_bf16_f32 v35, v38, v39
	v_pk_add_f32 v[38:39], v[40:41], v[36:37]
	v_cvt_pk_bf16_f32 v36, v40, v41
	v_pk_add_f32 v[40:41], v[44:45], v[64:65] op_sel_hi:[1,0] neg_lo:[0,1] neg_hi:[0,1]
	v_pk_add_f32 v[44:45], v[46:47], v[64:65] op_sel_hi:[1,0] neg_lo:[0,1] neg_hi:[0,1]
	v_exp_f32_e32 v40, v40
	v_exp_f32_e32 v41, v41
	v_exp_f32_e32 v44, v44
	v_exp_f32_e32 v45, v45
	v_pk_add_f32 v[38:39], v[42:43], v[38:39]
	v_cvt_pk_bf16_f32 v37, v42, v43
	s_nop 0
	v_pk_add_f32 v[42:43], v[40:41], v[38:39]
	v_cvt_pk_bf16_f32 v38, v40, v41
	v_cvt_pk_bf16_f32 v39, v44, v45
	s_nop 0
	v_pk_add_f32 v[40:41], v[44:45], v[42:43]
	v_pk_add_f32 v[16:17], v[16:17], v[64:65] op_sel_hi:[1,0] neg_lo:[0,1] neg_hi:[0,1]
	v_pk_add_f32 v[18:19], v[18:19], v[64:65] op_sel_hi:[1,0] neg_lo:[0,1] neg_hi:[0,1]
	v_exp_f32_e32 v16, v16
	v_exp_f32_e32 v17, v17
	v_exp_f32_e32 v18, v18
	v_exp_f32_e32 v19, v19
	v_pk_add_f32 v[20:21], v[20:21], v[64:65] op_sel_hi:[1,0] neg_lo:[0,1] neg_hi:[0,1]
	v_pk_add_f32 v[42:43], v[16:17], v[40:41]
	v_exp_f32_e32 v20, v20
	v_exp_f32_e32 v21, v21
	v_pk_add_f32 v[22:23], v[22:23], v[64:65] op_sel_hi:[1,0] neg_lo:[0,1] neg_hi:[0,1]
	v_cvt_pk_bf16_f32 v40, v16, v17
	v_pk_add_f32 v[16:17], v[18:19], v[42:43]
	v_exp_f32_e32 v22, v22
	v_exp_f32_e32 v23, v23
	v_cvt_pk_bf16_f32 v41, v18, v19
	v_pk_add_f32 v[18:19], v[24:25], v[64:65] op_sel_hi:[1,0] neg_lo:[0,1] neg_hi:[0,1]
	v_pk_add_f32 v[16:17], v[20:21], v[16:17]
	v_exp_f32_e32 v18, v18
	v_exp_f32_e32 v19, v19
	v_cvt_pk_bf16_f32 v42, v20, v21
	v_pk_add_f32 v[16:17], v[22:23], v[16:17]
	v_pk_add_f32 v[20:21], v[26:27], v[64:65] op_sel_hi:[1,0] neg_lo:[0,1] neg_hi:[0,1]
	v_cvt_pk_bf16_f32 v43, v22, v23
	v_pk_add_f32 v[16:17], v[18:19], v[16:17]
	v_exp_f32_e32 v20, v20
	v_exp_f32_e32 v21, v21
	v_cvt_pk_bf16_f32 v44, v18, v19
	v_pk_add_f32 v[18:19], v[28:29], v[64:65] op_sel_hi:[1,0] neg_lo:[0,1] neg_hi:[0,1]
	v_pk_add_f32 v[22:23], v[30:31], v[64:65] op_sel_hi:[1,0] neg_lo:[0,1] neg_hi:[0,1]
	v_exp_f32_e32 v18, v18
	v_exp_f32_e32 v19, v19
	v_exp_f32_e32 v22, v22
	v_exp_f32_e32 v23, v23
	v_pk_add_f32 v[16:17], v[20:21], v[16:17]
	v_cvt_pk_bf16_f32 v45, v20, v21
	v_cvt_pk_bf16_f32 v46, v18, v19
	v_cvt_pk_bf16_f32 v47, v22, v23
	s_nop 0
	v_pk_add_f32 v[16:17], v[18:19], v[16:17]
	s_nop 0
	v_pk_add_f32 v[16:17], v[22:23], v[16:17]
	v_pk_add_f32 v[0:1], v[0:1], v[64:65] op_sel_hi:[1,0] neg_lo:[0,1] neg_hi:[0,1]
	v_pk_add_f32 v[2:3], v[2:3], v[64:65] op_sel_hi:[1,0] neg_lo:[0,1] neg_hi:[0,1]
	v_exp_f32_e32 v0, v0
	v_exp_f32_e32 v1, v1
	v_exp_f32_e32 v2, v2
	v_exp_f32_e32 v3, v3
	v_pk_add_f32 v[4:5], v[4:5], v[64:65] op_sel_hi:[1,0] neg_lo:[0,1] neg_hi:[0,1]
	v_pk_add_f32 v[16:17], v[0:1], v[16:17]
	v_exp_f32_e32 v4, v4
	v_exp_f32_e32 v5, v5
	v_pk_add_f32 v[6:7], v[6:7], v[64:65] op_sel_hi:[1,0] neg_lo:[0,1] neg_hi:[0,1]
	v_cvt_pk_bf16_f32 v56, v0, v1
	v_pk_add_f32 v[0:1], v[2:3], v[16:17]
	v_exp_f32_e32 v6, v6
	v_exp_f32_e32 v7, v7
	v_cvt_pk_bf16_f32 v57, v2, v3
	v_pk_add_f32 v[2:3], v[8:9], v[64:65] op_sel_hi:[1,0] neg_lo:[0,1] neg_hi:[0,1]
	v_pk_add_f32 v[0:1], v[4:5], v[0:1]
	v_exp_f32_e32 v2, v2
	v_exp_f32_e32 v3, v3
	v_cvt_pk_bf16_f32 v58, v4, v5
	v_pk_add_f32 v[0:1], v[6:7], v[0:1]
	v_pk_add_f32 v[4:5], v[10:11], v[64:65] op_sel_hi:[1,0] neg_lo:[0,1] neg_hi:[0,1]
	v_cvt_pk_bf16_f32 v59, v6, v7
	v_pk_add_f32 v[0:1], v[2:3], v[0:1]
	v_exp_f32_e32 v4, v4
	v_exp_f32_e32 v5, v5
	v_cvt_pk_bf16_f32 v60, v2, v3
	v_pk_add_f32 v[2:3], v[12:13], v[64:65] op_sel_hi:[1,0] neg_lo:[0,1] neg_hi:[0,1]
	v_pk_add_f32 v[6:7], v[14:15], v[64:65] op_sel_hi:[1,0] neg_lo:[0,1] neg_hi:[0,1]
	v_exp_f32_e32 v2, v2
	v_exp_f32_e32 v3, v3
	v_exp_f32_e32 v6, v6
	v_exp_f32_e32 v7, v7
	v_pk_add_f32 v[0:1], v[4:5], v[0:1]
	v_cvt_pk_bf16_f32 v61, v4, v5
	v_cvt_pk_bf16_f32 v62, v2, v3
	v_cvt_pk_bf16_f32 v63, v6, v7
	s_nop 0
	v_pk_add_f32 v[0:1], v[2:3], v[0:1]
	s_nop 0
	v_pk_add_f32 v[0:1], v[6:7], v[0:1]
	v_pk_add_f32 v[2:3], v[152:153], v[64:65] op_sel_hi:[1,0] neg_lo:[0,1] neg_hi:[0,1]
	v_pk_add_f32 v[4:5], v[150:151], v[64:65] op_sel_hi:[1,0] neg_lo:[0,1] neg_hi:[0,1]
	v_exp_f32_e32 v2, v2
	v_exp_f32_e32 v3, v3
	v_exp_f32_e32 v4, v4
	v_exp_f32_e32 v5, v5
	v_cvt_pk_bf16_f32 v74, v2, v3
	v_pk_add_f32 v[0:1], v[2:3], v[0:1]
	v_pk_add_f32 v[2:3], v[148:149], v[64:65] op_sel_hi:[1,0] neg_lo:[0,1] neg_hi:[0,1]
	v_pk_add_f32 v[0:1], v[4:5], v[0:1]
	v_exp_f32_e32 v2, v2
	v_exp_f32_e32 v3, v3
	v_pk_add_f32 v[6:7], v[146:147], v[64:65] op_sel_hi:[1,0] neg_lo:[0,1] neg_hi:[0,1]
	v_cvt_pk_bf16_f32 v75, v4, v5
	v_cvt_pk_bf16_f32 v76, v2, v3
	v_pk_add_f32 v[0:1], v[2:3], v[0:1]
	v_exp_f32_e32 v6, v6
	v_exp_f32_e32 v7, v7
	v_pk_add_f32 v[2:3], v[72:73], v[64:65] op_sel_hi:[1,0] neg_lo:[0,1] neg_hi:[0,1]
	v_pk_add_f32 v[4:5], v[70:71], v[64:65] op_sel_hi:[1,0] neg_lo:[0,1] neg_hi:[0,1]
	v_exp_f32_e32 v2, v2
	v_exp_f32_e32 v3, v3
	v_pk_add_f32 v[0:1], v[6:7], v[0:1]
	v_exp_f32_e32 v4, v4
	v_exp_f32_e32 v5, v5
	v_cvt_pk_bf16_f32 v77, v6, v7
	v_pk_add_f32 v[0:1], v[2:3], v[0:1]
	v_cvt_pk_bf16_f32 v70, v2, v3
	v_pk_add_f32 v[2:3], v[68:69], v[64:65] op_sel_hi:[1,0] neg_lo:[0,1] neg_hi:[0,1]
	v_pk_add_f32 v[6:7], v[66:67], v[64:65] op_sel_hi:[1,0] neg_lo:[0,1] neg_hi:[0,1]
	v_exp_f32_e32 v2, v2
	v_exp_f32_e32 v3, v3
	v_exp_f32_e32 v6, v6
	v_exp_f32_e32 v7, v7
	v_pk_add_f32 v[0:1], v[4:5], v[0:1]
	v_cvt_pk_bf16_f32 v71, v4, v5
	v_cvt_pk_bf16_f32 v72, v2, v3
	v_cvt_pk_bf16_f32 v73, v6, v7
	s_nop 0
	v_pk_add_f32 v[0:1], v[2:3], v[0:1]
	s_nop 0
	v_pk_add_f32 v[78:79], v[6:7], v[0:1]
	ds_read_b64_tr_b16 v[0:1], v170 offset:55296
	ds_read_b64_tr_b16 v[2:3], v170 offset:56448
	ds_read_b64_tr_b16 v[18:19], v170 offset:56512
	ds_read_b64_tr_b16 v[16:17], v170 offset:55360
	s_waitcnt lgkmcnt(2)
	v_mfma_f32_32x32x16_bf16 v[0:15], v[48:51], v[0:3], 0
	s_waitcnt lgkmcnt(0)
	v_mfma_f32_32x32x16_bf16 v[16:31], v[48:51], v[16:19], 0
	ds_read_b64_tr_b16 v[48:49], v170 offset:57600
	ds_read_b64_tr_b16 v[50:51], v170 offset:58752
	ds_read_b64_tr_b16 v[68:69], v170 offset:58816
	ds_read_b64_tr_b16 v[66:67], v170 offset:57664
	s_waitcnt lgkmcnt(2)
	v_mfma_f32_32x32x16_bf16 v[0:15], v[52:55], v[48:51], v[0:15]
	s_waitcnt lgkmcnt(0)
	v_mfma_f32_32x32x16_bf16 v[16:31], v[52:55], v[66:69], v[16:31]
	ds_read_b64_tr_b16 v[48:49], v170 offset:59904
	ds_read_b64_tr_b16 v[50:51], v170 offset:61056
	ds_read_b64_tr_b16 v[54:55], v170 offset:61120
	ds_read_b64_tr_b16 v[52:53], v170 offset:59968
	s_waitcnt lgkmcnt(2)
	v_mfma_f32_32x32x16_bf16 v[0:15], v[32:35], v[48:51], v[0:15]
	s_waitcnt lgkmcnt(0)
	v_mfma_f32_32x32x16_bf16 v[16:31], v[32:35], v[52:55], v[16:31]
	ds_read_b64_tr_b16 v[32:33], v170 offset:62208
	ds_read_b64_tr_b16 v[34:35], v170 offset:63360
	ds_read_b64_tr_b16 v[50:51], v170 offset:63424
	ds_read_b64_tr_b16 v[48:49], v170 offset:62272
	s_waitcnt lgkmcnt(2)
	v_mfma_f32_32x32x16_bf16 v[0:15], v[36:39], v[32:35], v[0:15]
	s_waitcnt lgkmcnt(0)
	v_mfma_f32_32x32x16_bf16 v[16:31], v[36:39], v[48:51], v[16:31]
	ds_read_b64_tr_b16 v[32:33], v170 offset:64512
	ds_read_b64_tr_b16 v[34:35], v171 offset:10368
	ds_read_b64_tr_b16 v[38:39], v171 offset:10432
	ds_read_b64_tr_b16 v[36:37], v170 offset:64576
	s_waitcnt lgkmcnt(2)
	v_mfma_f32_32x32x16_bf16 v[0:15], v[40:43], v[32:35], v[0:15]
	s_waitcnt lgkmcnt(0)
	v_mfma_f32_32x32x16_bf16 v[16:31], v[40:43], v[36:39], v[16:31]
	ds_read_b64_tr_b16 v[32:33], v171 offset:11520
	ds_read_b64_tr_b16 v[34:35], v171 offset:12672
	ds_read_b64_tr_b16 v[38:39], v171 offset:12736
	ds_read_b64_tr_b16 v[36:37], v171 offset:11584
	s_waitcnt lgkmcnt(2)
	v_mfma_f32_32x32x16_bf16 v[0:15], v[44:47], v[32:35], v[0:15]
	s_waitcnt lgkmcnt(0)
	v_mfma_f32_32x32x16_bf16 v[16:31], v[44:47], v[36:39], v[16:31]
	ds_read_b64_tr_b16 v[32:33], v171 offset:13824
	ds_read_b64_tr_b16 v[34:35], v171 offset:14976
	ds_read_b64_tr_b16 v[38:39], v171 offset:15040
	ds_read_b64_tr_b16 v[36:37], v171 offset:13888
	s_waitcnt lgkmcnt(2)
	v_mfma_f32_32x32x16_bf16 v[0:15], v[56:59], v[32:35], v[0:15]
	s_waitcnt lgkmcnt(0)
	v_mfma_f32_32x32x16_bf16 v[16:31], v[56:59], v[36:39], v[16:31]
	ds_read_b64_tr_b16 v[32:33], v171 offset:16128
	ds_read_b64_tr_b16 v[34:35], v171 offset:17280
	ds_read_b64_tr_b16 v[38:39], v171 offset:17344
	ds_read_b64_tr_b16 v[36:37], v171 offset:16192
	s_waitcnt lgkmcnt(2)
	v_mfma_f32_32x32x16_bf16 v[0:15], v[60:63], v[32:35], v[0:15]
	s_waitcnt lgkmcnt(0)
	v_mfma_f32_32x32x16_bf16 v[16:31], v[60:63], v[36:39], v[16:31]
	ds_read_b64_tr_b16 v[32:33], v171 offset:18432
	ds_read_b64_tr_b16 v[34:35], v171 offset:19584
	ds_read_b64_tr_b16 v[38:39], v171 offset:19648
	ds_read_b64_tr_b16 v[36:37], v171 offset:18496
	s_waitcnt lgkmcnt(2)
	v_mfma_f32_32x32x16_bf16 v[0:15], v[74:77], v[32:35], v[0:15]
	s_waitcnt lgkmcnt(0)
	v_mfma_f32_32x32x16_bf16 v[16:31], v[74:77], v[36:39], v[16:31]
	ds_read_b64_tr_b16 v[32:33], v171 offset:20736
	ds_read_b64_tr_b16 v[34:35], v171 offset:21888
	ds_read_b64_tr_b16 v[38:39], v171 offset:21952
	ds_read_b64_tr_b16 v[36:37], v171 offset:20800
	s_waitcnt lgkmcnt(2)
	v_mfma_f32_32x32x16_bf16 v[0:15], v[70:73], v[32:35], v[0:15]
	v_add_f32_e32 v32, v78, v79
	ds_bpermute_b32 v33, v65, v32
	s_waitcnt lgkmcnt(1)
	v_mfma_f32_32x32x16_bf16 v[16:31], v[70:73], v[36:39], v[16:31]
	s_and_saveexec_b64 s[60:61], s[10:11]
	s_cbranch_execz .LBB0_1228
	v_sub_f32_e32 v34, v97, v64
	v_exp_f32_e32 v34, v34
	s_waitcnt lgkmcnt(0)
	v_add_f32_e32 v32, v32, v33
	v_add_f32_e32 v32, v34, v32
	v_div_scale_f32 v33, s[88:89], v32, v32, 1.0
	v_rcp_f32_e32 v34, v33
	v_div_scale_f32 v35, vcc, 1.0, v32, 1.0
	v_fma_f32 v36, -v33, v34, 1.0
	v_fmac_f32_e32 v34, v36, v34
	v_mul_f32_e32 v36, v35, v34
	v_fma_f32 v37, -v33, v36, v35
	v_fmac_f32_e32 v36, v37, v34
	v_fma_f32 v33, -v33, v36, v35
	v_div_fmas_f32 v33, v33, v34, v36
	v_div_fixup_f32 v32, v33, v32, 1.0
	ds_write_b32 v188, v32 offset:4608
	s_branch .LBB0_1228
